# XCD-local seam: arrive (drain + workgroup barrier + atomic) deferred to the next phase's body entry so the phase switch overlaps the store drain; GEMM-exit drain skipped where the arrive covers it
# baseline (speedup 1.0000x reference)
.LBB0_316:
	s_andn2_b64 vcc, exec, s[0:1]
	s_cbranch_vccnz .LBB0_511
	v_readlane_b32 s0, v232, 6
	s_cmp_eq_u32 s0, 1
	s_mov_b64 s[0:1], -1
	s_cbranch_scc1 .LBB0_486
	v_readlane_b32 vcc_lo, v232, 58
	s_cmp_lg_u32 vcc_lo, 2
	s_cbranch_scc1 .Lsa_done_g
	s_waitcnt vmcnt(0) lgkmcnt(0)
	s_barrier
	v_readfirstlane_b32 vcc_hi, v152
	s_cmp_lt_u32 vcc_hi, 64
	s_cbranch_scc0 .Lsa_set_g
	v_readlane_b32 s100, v234, 34
	v_readlane_b32 s101, v234, 35
	s_mov_b64 vcc, exec
	s_mov_b64 exec, 1
	v_mov_b32_e32 v211, 1
	s_nop 4
	global_atomic_add v210, v97, v211, s[100:101] sc0
	s_mov_b64 exec, vcc
.Lsa_set_g:
	s_mov_b32 vcc_lo, 1
	v_writelane_b32 v232, vcc_lo, 58
.Lsa_done_g:
	v_readlane_b32 s0, v233, 55
	v_readlane_b32 s50, v232, 8
	s_mul_i32 s34, s50, s0
	v_readlane_b32 s8, v235, 36
	v_mov_b32_e32 v12, v152
	s_cmp_lt_i32 s8, s34
	s_cselect_b64 s[0:1], -1, 0
	s_mov_b32 s54, s34
	s_cmp_ge_i32 s8, s34
	v_readfirstlane_b32 s38, v12
	s_cbranch_scc1 .LBB0_320
	s_lshl_b32 s8, s50, 2
	v_cvt_f32_u32_e32 v0, s8
	s_lshr_b32 s9, s54, 3
	v_readlane_b32 s34, v234, 40
	s_add_i32 s9, s9, s34
	v_rcp_iflag_f32_e32 v0, v0
	s_sub_i32 s34, 0, s8
	v_readlane_b32 s35, v234, 39
	s_mul_i32 s9, s9, s35
	v_mul_f32_e32 v0, 0x4f7ffffe, v0
	v_cvt_u32_f32_e32 v0, v0
	v_readlane_b32 s35, v235, 32
	s_add_i32 s9, s9, s35
	s_abs_i32 s39, s9
	v_readfirstlane_b32 s40, v0
	s_mul_i32 s34, s34, s40
	s_mul_hi_u32 s34, s40, s34
	s_add_i32 s40, s40, s34
	s_mul_hi_u32 s34, s39, s40
	s_mul_i32 s40, s34, s8
	s_sub_i32 s39, s39, s40
	s_ashr_i32 s35, s9, 31
	s_add_i32 s41, s34, 1
	s_sub_i32 s40, s39, s8
	s_cmp_ge_u32 s39, s8
	s_cselect_b32 s34, s41, s34
	s_cselect_b32 s39, s40, s39
	s_add_i32 s40, s34, 1
	s_cmp_ge_u32 s39, s8
	s_cselect_b32 s34, s40, s34
	s_xor_b32 s34, s34, s35
	s_sub_i32 s34, s34, s35
	s_lshl_b32 s35, s34, 2
	v_readlane_b32 s39, v233, 55
	s_sub_i32 s39, s39, s35
	s_min_i32 s39, s39, 4
	s_mul_i32 s34, s34, s8
	s_sext_i32_i16 s8, s39
	v_cvt_f32_i32_e32 v0, s8
	s_sub_i32 s34, s9, s34
	s_sext_i32_i16 s9, s34
	v_cvt_f32_i32_e32 v1, s9
	v_rcp_iflag_f32_e32 v2, v0
	s_xor_b32 s8, s9, s8
	s_ashr_i32 s8, s8, 30
	s_or_b32 s40, s8, 1
	v_mul_f32_e32 v2, v1, v2
	v_trunc_f32_e32 v2, v2
	v_fma_f32 v1, -v2, v0, v1
	v_cvt_i32_f32_e32 v2, v2
	v_cmp_ge_f32_e64 s[8:9], |v1|, |v0|
	s_and_b64 s[8:9], s[8:9], exec
	s_cselect_b32 s8, s40, 0
	v_readfirstlane_b32 s9, v2
	s_add_i32 s8, s9, s8
	s_sext_i32_i16 s69, s8
	s_mul_i32 s8, s8, s39
	s_sub_i32 s8, s34, s8
	s_sext_i32_i16 s8, s8
	s_add_i32 s46, s35, s8

.LBB0_398:
	v_readlane_b32 s86, v233, 26
	v_readlane_b32 s78, v232, 24
	v_readlane_b32 s87, v233, 27
	v_readlane_b32 s98, v233, 28
	v_readlane_b32 s64, v233, 31
	v_readlane_b32 s99, v233, 33
	v_readlane_b32 s70, v233, 34
	v_readlane_b32 s79, v232, 25
	v_readlane_b32 s76, v232, 22
	v_readlane_b32 s65, v233, 32
	v_readlane_b32 s77, v232, 23
	v_readlane_b32 s40, v233, 49
	s_lshr_b32 s40, 0x344244, s40
	s_and_b32 s40, s40, 1
	s_cmp_eq_u32 s40, 1
	s_cbranch_scc1 .LBB0_399
	s_waitcnt vmcnt(0)
	s_barrier

.LBB0_486:
	s_and_b64 vcc, exec, s[0:1]
	s_cbranch_vccz .LBB0_511
	v_readlane_b32 s0, v235, 30
	v_readlane_b32 s1, v232, 21
	s_add_i32 s8, s0, s1
	v_readlane_b32 s0, v236, 8
	v_readlane_b32 s1, v236, 9
	s_and_b64 s[0:1], s[0:1], exec
	s_cselect_b32 s8, s8, s76
	s_cmp_ge_i32 s8, s98
	s_cbranch_scc1 .LBB0_511
	v_readlane_b32 vcc_lo, v232, 58
	s_cmp_lg_u32 vcc_lo, 2
	s_cbranch_scc1 .Lsa_done_r
	s_waitcnt vmcnt(0) lgkmcnt(0)
	s_barrier
	v_readfirstlane_b32 vcc_hi, v152
	s_cmp_lt_u32 vcc_hi, 64
	s_cbranch_scc0 .Lsa_set_r
	v_readlane_b32 s100, v234, 34
	v_readlane_b32 s101, v234, 35
	s_mov_b64 vcc, exec
	s_mov_b64 exec, 1
	v_mov_b32_e32 v211, 1
	s_nop 4
	global_atomic_add v210, v97, v211, s[100:101] sc0
	s_mov_b64 exec, vcc

.LBB0_511:
	v_readlane_b32 vcc_lo, v232, 58
	s_cmp_lg_u32 vcc_lo, 2
	s_cbranch_scc1 .Lsa_done_e
	s_waitcnt vmcnt(0) lgkmcnt(0)
	s_barrier
	v_readfirstlane_b32 vcc_hi, v152
	s_cmp_lt_u32 vcc_hi, 64
	s_cbranch_scc0 .Lsa_set_e
	v_readlane_b32 s100, v234, 34
	v_readlane_b32 s101, v234, 35
	s_mov_b64 vcc, exec
	s_mov_b64 exec, 1
	v_mov_b32_e32 v211, 1
	s_nop 4
	global_atomic_add v210, v97, v211, s[100:101] sc0
	s_mov_b64 exec, vcc

.LBB0_566:
	v_readlane_b32 s8, v232, 13
	v_readlane_b32 s9, v232, 14
	s_and_b64 vcc, exec, s[8:9]
	s_cbranch_vccz .LBB0_586
	s_mov_b32 s8, 2
	v_writelane_b32 v232, s8, 58
	s_mov_b64 s[0:1], -1
